# class-major jobs: compacted conflict-free bias table together with the balanced query-tile rotation
# speedup vs baseline: 1.0000x; 1.0000x over previous
; DI int pi_row(int r) { return (r & 3) | (((r >> 3) & 1) << 2) | (((r >> 2) & 1) << 3) | (r & 16); }
; DI void load_lut(float* lut, const float* glut, int col, int lane) {
;     ...
;     f32x4 t[8];
; #pragma unroll
;     for (int k = 0; k < 8; ++k) t[k] = *(const f32x4*)(glut + (size_t)col * 2048 + k * 256 + lane * 4);
; #pragma unroll
;     for (int k = 0; k < 8; ++k) *(f32x4*)(lut + k * 256 + lane * 4) = t[k];
; DI void g2_job(const Args& a, unsigned char* wsh, LAS unsigned char* wl, int b, int slot, int cls, int it, const int tid) {
;     ...
;     float* lut = (float*)(wsh + 8192);
;     const int tok0 = b * SEQ;
;     const int d00 = 32 * it + r - 8 * h;
;     AttnCtx c; c.wl = wl; c.lut = lut; c.krs = 16;
; #pragma unroll
;     for (int j = 0; j < 4; ++j) {
;         const int rk = 8 * j + (lane >> 3), ck = (lane & 7) ^ ((rk >> 1) & 7);
;         c.koff[j] = (unsigned)(pi_row(rk) * 16 * RM_LD + ck * 8) * 2u;
;         const int rv = 16 * j + (lane >> 2), cv = (lane & 3) ^ ((rv >> 2) & 3);
;         c.voff[j] = (unsigned)(rv * MTOK + cv * 8) * 2u;
;         c.kfo[j] = r * 128 + (((2 * j + h) ^ ((r >> 1) & 7)) * 16);
;     }
; #pragma unroll
;     for (int mt = 0; mt < 2; ++mt)
; #pragma unroll
;         for (int s = 0; s < 2; ++s) c.vfo[mt][s] = (32 * mt + r) * 64 + (((2 * s + h) ^ ((r >> 2) & 3)) * 16);
;     AttnSt st; st.m = NEGF; st.l = 0.f;
; #pragma unroll
;     for (int i = 0; i < 16; ++i) { st.o0[i] = 0.f; st.o1[i] = 0.f; }
;     load_lut(lut, glut, 6 + 2 * 4 + slot, lane);
;     const int tq = tok0 + cls + 16 * (32 * it + r);
;     bf16x8 qf[4];
;     const bf16_t* qp = prm + (size_t)tq * RM_LD + C_BQ + (2 * 4 + slot) * 64 + 8 * h;
; #pragma unroll
;     for (int ks = 0; ks < 4; ++ks) qf[ks] = *(const bf16x8*)(qp + 16 * ks);
;     c.kg = prm + (size_t)(tok0 + cls) * RM_LD + C_BK + slot * 64;
;     c.vg = vt16 + (size_t)(slot * 64) * MTOK + tok0 + cls * 128;
;     attn_range<4>(c, qf, 0, it, 0, d00, st, nullptr, 0, 0, 0, false);
.LBB0_521:
	s_add_i32 s9, s8, 1
	v_and_b32_e32 v3, 31, v210
	v_lshrrev_b32_e32 v151, 2, v210
	v_lshl_or_b32 v3, s8, 5, v3
	v_and_b32_e32 v151, 8, v151
	s_add_i32 s98, s7, 0x1a40
	v_sub_u32_e32 v151, v3, v151
	v_lshlrev_b32_e32 v150, 4, v3
	v_lshl_add_u32 v152, v151, 6, s98
	s_lshl_b32 s0, s40, 17
	s_and_b32 s2, s0, 0x1800000
	s_and_b32 s0, s41, 0xfffff800
	s_bfe_u32 s43, s40, 0x40002
	s_ashr_i32 s1, s0, 31
	s_lshl_b32 s44, s43, 8
	s_lshl_b64 s[4:5], s[0:1], 1
	s_or_b32 s1, s4, s44
	s_add_u32 s4, s1, s2
	s_addc_u32 s5, s5, 0
	s_or_b32 s0, s0, s43
	s_lshl_b32 s2, s40, 1
	s_mul_hi_i32 s1, s0, 0x1600
	s_mulk_i32 s0, 0x1600
	s_and_b32 s2, s2, 0x180
	s_or_b32 s0, s0, s2
	v_lshl_add_u64 v[138:139], s[0:1], 0, v[120:121]
	v_lshl_add_u64 v[140:141], s[0:1], 0, v[122:123]
	v_lshl_add_u64 v[142:143], s[0:1], 0, v[124:125]
	v_lshl_add_u64 v[144:145], s[0:1], 0, v[126:127]
	s_lshl_b32 s0, s42, 3
	s_add_i32 s0, s0, s6
	s_bfe_u32 s43, s0, 0x20006
	s_bfe_u32 s45, s0, 0x40002
	s_lshl_b32 s0, s0, 3
	s_and_b32 s0, s0, 0xfffff800
	s_lshl_b32 s1, s43, 13
	v_lshl_add_u64 v[130:131], s[4:5], 0, v[100:101]
	v_lshl_add_u64 v[132:133], s[4:5], 0, v[114:115]
	v_lshl_add_u64 v[134:135], s[4:5], 0, v[116:117]
	v_lshl_add_u64 v[136:137], s[4:5], 0, v[118:119]
	s_add_u32 s4, s92, s1
	s_addc_u32 s5, s93, 0
	v_lshl_add_u64 v[2:3], s[4:5], 0, v[0:1]
	s_mov_b32 s1, 0x471d000
	s_mov_b64 s[4:5], 0x471c000
	v_add_co_u32_e32 v30, vcc, s1, v2
	v_lshl_add_u64 v[14:15], v[2:3], 0, s[4:5]
	s_nop 0
	v_addc_co_u32_e32 v31, vcc, 0, v3, vcc
	global_load_dwordx4 v[2:5], v[30:31], off offset:-4096
	global_load_dwordx4 v[6:9], v[14:15], off offset:1024
	global_load_dwordx4 v[10:13], v[14:15], off offset:2048
	s_nop 0
	global_load_dwordx4 v[14:17], v[14:15], off offset:3072
	s_nop 0
	global_load_dwordx4 v[18:21], v[30:31], off
	global_load_dwordx4 v[22:25], v[30:31], off offset:1024
	global_load_dwordx4 v[26:29], v[30:31], off offset:2048
	s_nop 0
	global_load_dwordx4 v[30:33], v[30:31], off offset:3072
	v_readlane_b32 s46, v254, 55
	s_or_b32 s1, s45, s0
	v_readlane_b32 s47, v254, 56
	v_or_b32_e32 v146, s1, v150
	s_movk_i32 s2, 0x1600
	v_mov_b32_e32 v99, v1
	s_mov_b32 m0, s7
	s_mov_b32 s44, 0
	v_ashrrev_i32_e32 v147, 31, v146
	v_mov_b32_e32 v160, 0xf149f2ca
	s_add_i32 s98, s7, 0x1fa4
	v_lshl_add_u32 v129, v151, 2, s98
	v_mov_b32_e32 v159, v151
	s_waitcnt vmcnt(0)
	v_subrev_u32_e32 v161, s7, v149
	s_add_i32 s98, s7, 0x2000
	v_lshrrev_b32_e32 v161, 4, v161
	v_add_u32_e32 v161, s98, v161
	s_mov_b64 s[98:99], exec
	s_mov_b32 exec_lo, 0x11111111
	s_mov_b32 exec_hi, 0x11111111
	ds_write_b32 v161, v2
	ds_write_b32 v161, v6 offset:64
	ds_write_b32 v161, v10 offset:128
	ds_write_b32 v161, v14 offset:192
	ds_write_b32 v161, v18 offset:256
	ds_write_b32 v161, v22 offset:320
	ds_write_b32 v161, v26 offset:384
	ds_write_b32 v161, v30 offset:448
	s_mov_b64 exec, s[98:99]
	v_mov_b64_e32 v[2:3], s[46:47]
	v_mad_i64_i32 v[2:3], s[4:5], v146, s2, v[2:3]
	s_lshl_b32 s2, s43, 7
	s_mul_hi_i32 s4, s1, 0x1600
	s_mulk_i32 s1, 0x1600
	s_add_u32 s1, s46, s1
	s_addc_u32 s5, s47, s4
	s_add_u32 s4, s1, s2
	s_addc_u32 s5, s5, 0
	s_lshl_b32 s1, s43, 23
	v_readlane_b32 s46, v251, 32
	v_lshl_add_u64 v[2:3], v[2:3], 0, s[2:3]
	v_readlane_b32 s47, v251, 33
	s_add_u32 s2, s46, s1
	s_addc_u32 s46, s47, 0
	s_ashr_i32 s1, s0, 31
	s_lshl_b64 s[0:1], s[0:1], 1
	v_lshl_add_u64 v[2:3], v[2:3], 0, v[98:99]
	s_add_u32 s0, s2, s0
	global_load_dwordx4 v[50:53], v[2:3], off offset:3072
	global_load_dwordx4 v[54:57], v[2:3], off offset:3104
	global_load_dwordx4 v[58:61], v[2:3], off offset:3136
	global_load_dwordx4 v[62:65], v[2:3], off offset:3168
	s_addc_u32 s1, s46, s1
	s_lshl_b32 s2, s45, 8
	v_lshl_add_u64 v[2:3], s[4:5], 0, v[96:97]
	s_add_u32 s0, s0, s2
	v_lshl_add_u64 v[2:3], v[2:3], 0, s[20:21]
	s_addc_u32 s1, s1, 0
	global_load_lds_dwordx4 v[2:3], off
	v_lshl_add_u64 v[2:3], s[4:5], 0, v[102:103]
	s_add_i32 s2, s7, 0x400
	v_lshl_add_u64 v[2:3], v[2:3], 0, s[20:21]
	s_mov_b32 m0, s2
	s_add_i32 s45, s7, 0x800
	global_load_lds_dwordx4 v[2:3], off
	v_lshl_add_u64 v[2:3], s[4:5], 0, v[106:107]
	v_lshl_add_u64 v[2:3], v[2:3], 0, s[20:21]
	s_mov_b32 m0, s45
	s_add_i32 s46, s7, 0x1400
	global_load_lds_dwordx4 v[2:3], off
	v_lshl_add_u64 v[2:3], s[4:5], 0, v[110:111]
	s_add_i32 s4, s7, 0xc00
	v_lshl_add_u64 v[2:3], v[2:3], 0, s[20:21]
	s_mov_b32 m0, s4
	s_add_i32 s5, s7, 0x1000
	global_load_lds_dwordx4 v[2:3], off
	v_lshl_add_u64 v[2:3], s[0:1], 0, v[94:95]
	s_mov_b32 m0, s5
	s_add_i32 s47, s7, 0x1800
	global_load_lds_dwordx4 v[2:3], off
	v_lshl_add_u64 v[2:3], s[0:1], 0, v[104:105]
	s_mov_b32 m0, s46
	v_mov_b32_e32 v16, v1
	global_load_lds_dwordx4 v[2:3], off
	v_lshl_add_u64 v[2:3], s[0:1], 0, v[108:109]
	s_mov_b32 m0, s47
	v_mov_b32_e32 v17, v1
	global_load_lds_dwordx4 v[2:3], off
	v_lshl_add_u64 v[2:3], s[0:1], 0, v[112:113]
	s_add_i32 s0, s7, 0x1c00
	s_mov_b32 m0, s0
	v_mov_b32_e32 v4, v1
	global_load_lds_dwordx4 v[2:3], off
	v_mov_b32_e32 v2, v1
	v_mov_b32_e32 v3, v1
	v_mov_b32_e32 v5, v1
	v_mov_b32_e32 v6, v1
	v_mov_b32_e32 v7, v1
	v_mov_b32_e32 v8, v1
	v_mov_b32_e32 v9, v1
	v_mov_b32_e32 v10, v1
	v_mov_b32_e32 v11, v1
	v_mov_b32_e32 v12, v1
	v_mov_b32_e32 v13, v1
	v_mov_b32_e32 v14, v1
	v_mov_b32_e32 v15, v1
	v_mov_b64_e32 v[32:33], v[16:17]
	v_mov_b32_e32 v99, 0
	v_mov_b64_e32 v[30:31], v[14:15]
	v_mov_b64_e32 v[28:29], v[12:13]
	v_mov_b64_e32 v[26:27], v[10:11]
	v_mov_b64_e32 v[24:25], v[8:9]
	v_mov_b64_e32 v[22:23], v[6:7]
	v_mov_b64_e32 v[20:21], v[4:5]
	v_mov_b64_e32 v[18:19], v[2:3]
	s_waitcnt vmcnt(0)
